# GEMM K-loops: per-phase s_setprio flips deleted (A/B of the 8-phase template's priority toggling)
# speedup vs baseline: 1.0002x; 1.0002x over previous
.LBB0_470:
	s_add_i32 s52, s8, 2
	s_add_u32 s53, s6, 0x80
	s_addc_u32 s9, s7, 0
	s_add_i32 s79, 0, 0x10000
	s_cmp_eq_u32 s73, s8
	s_cselect_b32 s9, s23, s9
	s_cselect_b32 s8, s22, s53
	s_cselect_b32 s81, s25, s78
	s_cselect_b32 s80, s24, s77
	s_add_i32 s53, 0, 0x14000
	v_add_u32_e32 v68, s79, v195
	v_add_u32_e32 v152, s53, v195
	ds_read_b128 v[56:59], v68
	ds_read_b128 v[60:63], v68 offset:1024
	ds_read_b128 v[64:67], v68 offset:2048
	ds_read_b128 v[68:71], v68 offset:3072
	ds_read_b128 v[144:147], v152
	ds_read_b128 v[148:151], v152 offset:1024
	ds_read_b128 v[170:173], v152 offset:2048
	ds_read_b128 v[174:177], v152 offset:3072
	v_lshl_add_u64 v[184:185], s[6:7], 0, v[168:169]
	s_add_i32 m0, s64, 0xc000
	ds_read_b128 v[178:181], v197
	ds_read_b128 v[198:201], v197 offset:1024
	ds_read_b128 v[202:205], v197 offset:2048
	ds_read_b128 v[206:209], v197 offset:3072
	ds_read_b128 v[210:213], v197 offset:4096
	ds_read_b128 v[214:217], v197 offset:5120
	ds_read_b128 v[218:221], v197 offset:6144
	ds_read_b128 v[222:225], v197 offset:7168
	global_load_lds_dwordx4 v[184:185], off
	v_lshl_add_u64 v[184:185], s[6:7], 0, v[166:167]
	s_add_i32 m0, s64, 0xe000
	s_nop 0
	global_load_lds_dwordx4 v[184:185], off
	s_waitcnt vmcnt(8)
	s_waitcnt lgkmcnt(0)
	s_barrier
	s_waitcnt lgkmcnt(0)
	v_mfma_f32_16x16x32_bf16 v[140:143], v[56:59], v[178:181], v[140:143]
	v_mfma_f32_16x16x32_bf16 v[136:139], v[64:67], v[178:181], v[136:139]
	v_mfma_f32_16x16x32_bf16 v[124:127], v[56:59], v[202:205], v[124:127]
	v_mfma_f32_16x16x32_bf16 v[120:123], v[64:67], v[202:205], v[120:123]
	v_mfma_f32_16x16x32_bf16 v[108:111], v[56:59], v[210:213], v[108:111]
	v_mfma_f32_16x16x32_bf16 v[104:107], v[64:67], v[210:213], v[104:107]
	v_mfma_f32_16x16x32_bf16 v[92:95], v[56:59], v[218:221], v[92:95]
	v_mfma_f32_16x16x32_bf16 v[88:91], v[64:67], v[218:221], v[88:91]
	v_mfma_f32_16x16x32_bf16 v[140:143], v[60:63], v[198:201], v[140:143]
	v_mfma_f32_16x16x32_bf16 v[136:139], v[68:71], v[198:201], v[136:139]
	v_mfma_f32_16x16x32_bf16 v[124:127], v[60:63], v[206:209], v[124:127]
	v_mfma_f32_16x16x32_bf16 v[120:123], v[68:71], v[206:209], v[120:123]
	v_mfma_f32_16x16x32_bf16 v[108:111], v[60:63], v[214:217], v[108:111]
	v_mfma_f32_16x16x32_bf16 v[104:107], v[68:71], v[214:217], v[104:107]
	v_mfma_f32_16x16x32_bf16 v[92:95], v[60:63], v[222:225], v[92:95]
	v_mfma_f32_16x16x32_bf16 v[88:91], v[68:71], v[222:225], v[88:91]
	v_mfma_f32_16x16x32_bf16 v[132:135], v[144:147], v[178:181], v[132:135]
	v_mfma_f32_16x16x32_bf16 v[128:131], v[170:173], v[178:181], v[128:131]
	v_mfma_f32_16x16x32_bf16 v[116:119], v[144:147], v[202:205], v[116:119]
	v_mfma_f32_16x16x32_bf16 v[112:115], v[170:173], v[202:205], v[112:115]
	v_mfma_f32_16x16x32_bf16 v[100:103], v[144:147], v[210:213], v[100:103]
	v_mfma_f32_16x16x32_bf16 v[96:99], v[170:173], v[210:213], v[96:99]
	v_mfma_f32_16x16x32_bf16 v[84:87], v[144:147], v[218:221], v[84:87]
	v_mfma_f32_16x16x32_bf16 v[80:83], v[170:173], v[218:221], v[80:83]
	v_mfma_f32_16x16x32_bf16 v[132:135], v[148:151], v[198:201], v[132:135]
	v_mfma_f32_16x16x32_bf16 v[128:131], v[174:177], v[198:201], v[128:131]
	v_mfma_f32_16x16x32_bf16 v[116:119], v[148:151], v[206:209], v[116:119]
	v_mfma_f32_16x16x32_bf16 v[112:115], v[174:177], v[206:209], v[112:115]
	v_mfma_f32_16x16x32_bf16 v[100:103], v[148:151], v[214:217], v[100:103]
	v_mfma_f32_16x16x32_bf16 v[96:99], v[174:177], v[214:217], v[96:99]
	v_mfma_f32_16x16x32_bf16 v[84:87], v[148:151], v[222:225], v[84:87]
	v_mfma_f32_16x16x32_bf16 v[80:83], v[174:177], v[222:225], v[80:83]
	s_barrier
	s_add_i32 s79, s79, s55
	v_lshl_add_u64 v[184:185], s[80:81], 0, v[162:163]
	s_mov_b32 m0, s79
	ds_read_b128 v[178:181], v197 offset:16384
	ds_read_b128 v[198:201], v197 offset:17408
	ds_read_b128 v[202:205], v197 offset:18432
	ds_read_b128 v[206:209], v197 offset:19456
	ds_read_b128 v[210:213], v197 offset:20480
	ds_read_b128 v[214:217], v197 offset:21504
	ds_read_b128 v[218:221], v197 offset:22528
	ds_read_b128 v[222:225], v197 offset:23552
	global_load_lds_dwordx4 v[184:185], off
	s_add_i32 m0, s79, 0x2000
	v_lshl_add_u64 v[226:227], s[80:81], 0, v[158:159]
	s_add_u32 s80, s80, s14
	s_addc_u32 s81, s81, 0
	s_add_i32 s53, s53, s55
	global_load_lds_dwordx4 v[226:227], off
	v_lshl_add_u64 v[228:229], s[80:81], 0, v[162:163]
	s_mov_b32 m0, s53
	v_lshl_add_u64 v[230:231], s[80:81], 0, v[158:159]
	global_load_lds_dwordx4 v[228:229], off
	s_add_i32 m0, s53, 0x2000
	v_lshl_add_u64 v[232:233], s[8:9], 0, v[164:165]
	global_load_lds_dwordx4 v[230:231], off
	s_mov_b32 m0, s64
	v_lshl_add_u64 v[234:235], s[8:9], 0, v[160:161]
	global_load_lds_dwordx4 v[232:233], off
	s_mov_b32 m0, s65
	s_nop 0
	global_load_lds_dwordx4 v[234:235], off
	s_waitcnt vmcnt(8)
	s_waitcnt lgkmcnt(0)
	s_barrier
	s_waitcnt lgkmcnt(0)
	v_mfma_f32_16x16x32_bf16 v[76:79], v[56:59], v[178:181], v[76:79]
	v_mfma_f32_16x16x32_bf16 v[72:75], v[64:67], v[178:181], v[72:75]
	v_mfma_f32_16x16x32_bf16 v[44:47], v[56:59], v[202:205], v[44:47]
	v_mfma_f32_16x16x32_bf16 v[40:43], v[64:67], v[202:205], v[40:43]
	v_mfma_f32_16x16x32_bf16 v[28:31], v[56:59], v[210:213], v[28:31]
	v_mfma_f32_16x16x32_bf16 v[24:27], v[64:67], v[210:213], v[24:27]
	v_mfma_f32_16x16x32_bf16 v[12:15], v[56:59], v[218:221], v[12:15]
	v_mfma_f32_16x16x32_bf16 v[8:11], v[64:67], v[218:221], v[8:11]
	v_mfma_f32_16x16x32_bf16 v[76:79], v[60:63], v[198:201], v[76:79]
	v_mfma_f32_16x16x32_bf16 v[72:75], v[68:71], v[198:201], v[72:75]
	v_mfma_f32_16x16x32_bf16 v[44:47], v[60:63], v[206:209], v[44:47]
	v_mfma_f32_16x16x32_bf16 v[40:43], v[68:71], v[206:209], v[40:43]
	v_mfma_f32_16x16x32_bf16 v[28:31], v[60:63], v[214:217], v[28:31]
	v_mfma_f32_16x16x32_bf16 v[24:27], v[68:71], v[214:217], v[24:27]
	v_mfma_f32_16x16x32_bf16 v[12:15], v[60:63], v[222:225], v[12:15]
	v_mfma_f32_16x16x32_bf16 v[8:11], v[68:71], v[222:225], v[8:11]
	v_mfma_f32_16x16x32_bf16 v[52:55], v[144:147], v[178:181], v[52:55]
	v_mfma_f32_16x16x32_bf16 v[48:51], v[170:173], v[178:181], v[48:51]
	v_mfma_f32_16x16x32_bf16 v[36:39], v[144:147], v[202:205], v[36:39]
	v_mfma_f32_16x16x32_bf16 v[32:35], v[170:173], v[202:205], v[32:35]
	v_mfma_f32_16x16x32_bf16 v[20:23], v[144:147], v[210:213], v[20:23]
	v_mfma_f32_16x16x32_bf16 v[16:19], v[170:173], v[210:213], v[16:19]
	v_mfma_f32_16x16x32_bf16 v[4:7], v[144:147], v[218:221], v[4:7]
	v_mfma_f32_16x16x32_bf16 v[0:3], v[170:173], v[218:221], v[0:3]
	v_mfma_f32_16x16x32_bf16 v[52:55], v[148:151], v[198:201], v[52:55]
	v_mfma_f32_16x16x32_bf16 v[48:51], v[174:177], v[198:201], v[48:51]
	v_mfma_f32_16x16x32_bf16 v[36:39], v[148:151], v[206:209], v[36:39]
	v_mfma_f32_16x16x32_bf16 v[32:35], v[174:177], v[206:209], v[32:35]
	v_mfma_f32_16x16x32_bf16 v[20:23], v[148:151], v[214:217], v[20:23]
	v_mfma_f32_16x16x32_bf16 v[16:19], v[174:177], v[214:217], v[16:19]
	v_mfma_f32_16x16x32_bf16 v[4:7], v[148:151], v[222:225], v[4:7]
	v_mfma_f32_16x16x32_bf16 v[0:3], v[174:177], v[222:225], v[0:3]
	s_barrier
	s_add_i32 s53, 0, 0x18000
	s_add_i32 s79, 0, 0x1c000
	v_add_u32_e32 v68, s53, v195
	v_add_u32_e32 v152, s79, v195
	ds_read_b128 v[56:59], v68
	ds_read_b128 v[60:63], v68 offset:1024
	ds_read_b128 v[64:67], v68 offset:2048
	ds_read_b128 v[68:71], v68 offset:3072
	ds_read_b128 v[144:147], v152
	ds_read_b128 v[148:151], v152 offset:1024
	ds_read_b128 v[170:173], v152 offset:2048
	ds_read_b128 v[174:177], v152 offset:3072
	s_add_u32 s8, s8, s14
	s_addc_u32 s9, s9, 0
	s_mov_b32 m0, s66
	v_lshl_add_u64 v[236:237], s[8:9], 0, v[164:165]
	ds_read_b128 v[178:181], v197 offset:32768
	ds_read_b128 v[198:201], v197 offset:33792
	ds_read_b128 v[202:205], v197 offset:34816
	ds_read_b128 v[206:209], v197 offset:35840
	ds_read_b128 v[210:213], v197 offset:36864
	ds_read_b128 v[214:217], v197 offset:37888
	ds_read_b128 v[218:221], v197 offset:38912
	ds_read_b128 v[222:225], v197 offset:39936
	global_load_lds_dwordx4 v[236:237], off
	v_lshl_add_u64 v[236:237], s[8:9], 0, v[160:161]
	s_mov_b32 m0, s67
	s_nop 0
	global_load_lds_dwordx4 v[236:237], off
	s_waitcnt vmcnt(8)
	s_waitcnt lgkmcnt(0)
	s_barrier
	s_waitcnt lgkmcnt(0)
	v_mfma_f32_16x16x32_bf16 v[140:143], v[56:59], v[178:181], v[140:143]
	v_mfma_f32_16x16x32_bf16 v[136:139], v[64:67], v[178:181], v[136:139]
	v_mfma_f32_16x16x32_bf16 v[124:127], v[56:59], v[202:205], v[124:127]
	v_mfma_f32_16x16x32_bf16 v[120:123], v[64:67], v[202:205], v[120:123]
	v_mfma_f32_16x16x32_bf16 v[108:111], v[56:59], v[210:213], v[108:111]
	v_mfma_f32_16x16x32_bf16 v[104:107], v[64:67], v[210:213], v[104:107]
	v_mfma_f32_16x16x32_bf16 v[92:95], v[56:59], v[218:221], v[92:95]
	v_mfma_f32_16x16x32_bf16 v[88:91], v[64:67], v[218:221], v[88:91]
	v_mfma_f32_16x16x32_bf16 v[140:143], v[60:63], v[198:201], v[140:143]
	v_mfma_f32_16x16x32_bf16 v[136:139], v[68:71], v[198:201], v[136:139]
	v_mfma_f32_16x16x32_bf16 v[124:127], v[60:63], v[206:209], v[124:127]
	v_mfma_f32_16x16x32_bf16 v[120:123], v[68:71], v[206:209], v[120:123]
	v_mfma_f32_16x16x32_bf16 v[108:111], v[60:63], v[214:217], v[108:111]
	v_mfma_f32_16x16x32_bf16 v[104:107], v[68:71], v[214:217], v[104:107]
	v_mfma_f32_16x16x32_bf16 v[92:95], v[60:63], v[222:225], v[92:95]
	v_mfma_f32_16x16x32_bf16 v[88:91], v[68:71], v[222:225], v[88:91]
	v_mfma_f32_16x16x32_bf16 v[132:135], v[144:147], v[178:181], v[132:135]
	v_mfma_f32_16x16x32_bf16 v[128:131], v[170:173], v[178:181], v[128:131]
	v_mfma_f32_16x16x32_bf16 v[116:119], v[144:147], v[202:205], v[116:119]
	v_mfma_f32_16x16x32_bf16 v[112:115], v[170:173], v[202:205], v[112:115]
	v_mfma_f32_16x16x32_bf16 v[100:103], v[144:147], v[210:213], v[100:103]
	v_mfma_f32_16x16x32_bf16 v[96:99], v[170:173], v[210:213], v[96:99]
	v_mfma_f32_16x16x32_bf16 v[84:87], v[144:147], v[218:221], v[84:87]
	v_mfma_f32_16x16x32_bf16 v[80:83], v[170:173], v[218:221], v[80:83]
	v_mfma_f32_16x16x32_bf16 v[132:135], v[148:151], v[198:201], v[132:135]
	v_mfma_f32_16x16x32_bf16 v[128:131], v[174:177], v[198:201], v[128:131]
	v_mfma_f32_16x16x32_bf16 v[116:119], v[148:151], v[206:209], v[116:119]
	v_mfma_f32_16x16x32_bf16 v[112:115], v[174:177], v[206:209], v[112:115]
	v_mfma_f32_16x16x32_bf16 v[100:103], v[148:151], v[214:217], v[100:103]
	v_mfma_f32_16x16x32_bf16 v[96:99], v[174:177], v[214:217], v[96:99]
	v_mfma_f32_16x16x32_bf16 v[84:87], v[148:151], v[222:225], v[84:87]
	v_mfma_f32_16x16x32_bf16 v[80:83], v[174:177], v[222:225], v[80:83]
	s_barrier
	s_add_i32 s8, s53, s55
	v_lshl_add_u64 v[184:185], v[184:185], 0, s[26:27]
	s_mov_b32 m0, s8
	ds_read_b128 v[178:181], v197 offset:49152
	ds_read_b128 v[198:201], v197 offset:50176
	ds_read_b128 v[202:205], v197 offset:51200
	ds_read_b128 v[206:209], v197 offset:52224
	ds_read_b128 v[210:213], v197 offset:53248
	ds_read_b128 v[214:217], v197 offset:54272
	ds_read_b128 v[218:221], v197 offset:55296
	ds_read_b128 v[222:225], v197 offset:56320
	global_load_lds_dwordx4 v[184:185], off
	v_lshl_add_u64 v[184:185], v[226:227], 0, s[26:27]
	s_add_i32 m0, s8, 0x2000
	s_add_i32 s8, s79, s55
	global_load_lds_dwordx4 v[184:185], off
	v_lshl_add_u64 v[184:185], v[228:229], 0, s[26:27]
	s_mov_b32 m0, s8
	s_nop 0
	global_load_lds_dwordx4 v[184:185], off
	v_lshl_add_u64 v[184:185], v[230:231], 0, s[26:27]
	s_add_i32 m0, s8, 0x2000
	s_nop 0
	global_load_lds_dwordx4 v[184:185], off
	v_lshl_add_u64 v[184:185], v[232:233], 0, s[26:27]
	s_mov_b32 m0, s71
	s_nop 0
	global_load_lds_dwordx4 v[184:185], off
	v_lshl_add_u64 v[184:185], v[234:235], 0, s[26:27]
	s_mov_b32 m0, s72
	s_nop 0
	global_load_lds_dwordx4 v[184:185], off
	s_waitcnt vmcnt(8)
	s_waitcnt lgkmcnt(0)
	s_barrier
	s_waitcnt lgkmcnt(0)
	v_mfma_f32_16x16x32_bf16 v[76:79], v[56:59], v[178:181], v[76:79]
	v_mfma_f32_16x16x32_bf16 v[72:75], v[64:67], v[178:181], v[72:75]
	v_mfma_f32_16x16x32_bf16 v[44:47], v[56:59], v[202:205], v[44:47]
	v_mfma_f32_16x16x32_bf16 v[40:43], v[64:67], v[202:205], v[40:43]
	v_mfma_f32_16x16x32_bf16 v[28:31], v[56:59], v[210:213], v[28:31]
	v_mfma_f32_16x16x32_bf16 v[24:27], v[64:67], v[210:213], v[24:27]
	v_mfma_f32_16x16x32_bf16 v[12:15], v[56:59], v[218:221], v[12:15]
	v_mfma_f32_16x16x32_bf16 v[8:11], v[64:67], v[218:221], v[8:11]
	v_mfma_f32_16x16x32_bf16 v[76:79], v[60:63], v[198:201], v[76:79]
	v_mfma_f32_16x16x32_bf16 v[72:75], v[68:71], v[198:201], v[72:75]
	v_mfma_f32_16x16x32_bf16 v[44:47], v[60:63], v[206:209], v[44:47]
	v_mfma_f32_16x16x32_bf16 v[40:43], v[68:71], v[206:209], v[40:43]
	v_mfma_f32_16x16x32_bf16 v[28:31], v[60:63], v[214:217], v[28:31]
	v_mfma_f32_16x16x32_bf16 v[24:27], v[68:71], v[214:217], v[24:27]
	v_mfma_f32_16x16x32_bf16 v[12:15], v[60:63], v[222:225], v[12:15]
	v_mfma_f32_16x16x32_bf16 v[8:11], v[68:71], v[222:225], v[8:11]
	v_mfma_f32_16x16x32_bf16 v[52:55], v[144:147], v[178:181], v[52:55]
	v_mfma_f32_16x16x32_bf16 v[48:51], v[170:173], v[178:181], v[48:51]
	v_mfma_f32_16x16x32_bf16 v[36:39], v[144:147], v[202:205], v[36:39]
	v_mfma_f32_16x16x32_bf16 v[32:35], v[170:173], v[202:205], v[32:35]
	v_mfma_f32_16x16x32_bf16 v[20:23], v[144:147], v[210:213], v[20:23]
	v_mfma_f32_16x16x32_bf16 v[16:19], v[170:173], v[210:213], v[16:19]
	v_mfma_f32_16x16x32_bf16 v[4:7], v[144:147], v[218:221], v[4:7]
	v_mfma_f32_16x16x32_bf16 v[0:3], v[170:173], v[218:221], v[0:3]
	v_mfma_f32_16x16x32_bf16 v[52:55], v[148:151], v[198:201], v[52:55]
	v_mfma_f32_16x16x32_bf16 v[48:51], v[174:177], v[198:201], v[48:51]
	v_mfma_f32_16x16x32_bf16 v[36:39], v[148:151], v[206:209], v[36:39]
	v_mfma_f32_16x16x32_bf16 v[32:35], v[174:177], v[206:209], v[32:35]
	v_mfma_f32_16x16x32_bf16 v[20:23], v[148:151], v[214:217], v[20:23]
	v_mfma_f32_16x16x32_bf16 v[16:19], v[174:177], v[214:217], v[16:19]
	v_mfma_f32_16x16x32_bf16 v[4:7], v[148:151], v[222:225], v[4:7]
	v_mfma_f32_16x16x32_bf16 v[0:3], v[174:177], v[222:225], v[0:3]
	s_barrier
	s_add_u32 s77, s77, 0x100
	s_addc_u32 s78, s78, 0
	s_add_u32 s6, s6, 0x100
	s_addc_u32 s7, s7, 0
	s_cmp_ge_u32 s52, s69
	s_mov_b32 s8, s52
	s_cbranch_scc0 .LBB0_470
	s_and_b64 vcc, exec, s[18:19]
	s_cbranch_vccz .LBB0_473
	s_barrier

.LBB0_589:
	s_add_i32 s24, s22, 2
	s_add_u32 s25, s4, 0x80
	s_addc_u32 s23, s5, 0
	s_add_i32 s75, 0, 0x10000
	s_cmp_eq_u32 s64, s22
	s_cselect_b32 s23, s19, s23
	s_cselect_b32 s22, s18, s25
	s_cselect_b32 s77, s21, s74
	s_cselect_b32 s76, s20, s73
	s_add_i32 s25, 0, 0x14000
	v_add_u32_e32 v36, s75, v203
	v_add_u32_e32 v172, s25, v203
	ds_read_b128 v[24:27], v36
	ds_read_b128 v[28:31], v36 offset:1024
	ds_read_b128 v[32:35], v36 offset:2048
	ds_read_b128 v[36:39], v36 offset:3072
	ds_read_b128 v[160:163], v172
	ds_read_b128 v[164:167], v172 offset:1024
	ds_read_b128 v[168:171], v172 offset:2048
	ds_read_b128 v[206:209], v172 offset:3072
	v_lshl_add_u64 v[172:173], s[4:5], 0, v[158:159]
	s_add_i32 m0, s45, 0xc000
	ds_read_b128 v[210:213], v205
	ds_read_b128 v[214:217], v205 offset:1024
	ds_read_b128 v[218:221], v205 offset:2048
	ds_read_b128 v[222:225], v205 offset:3072
	ds_read_b128 v[226:229], v205 offset:4096
	ds_read_b128 v[230:233], v205 offset:5120
	ds_read_b128 v[234:237], v205 offset:6144
	ds_read_b128 v[238:241], v205 offset:7168
	global_load_lds_dwordx4 v[172:173], off
	v_lshl_add_u64 v[172:173], s[4:5], 0, v[150:151]
	s_add_i32 m0, s45, 0xe000
	s_nop 0
	global_load_lds_dwordx4 v[172:173], off
	s_waitcnt vmcnt(8)
	s_waitcnt lgkmcnt(0)
	s_barrier
	s_waitcnt lgkmcnt(0)
	v_mfma_f32_16x16x32_bf16 v[140:143], v[24:27], v[210:213], v[140:143]
	v_mfma_f32_16x16x32_bf16 v[136:139], v[32:35], v[210:213], v[136:139]
	v_mfma_f32_16x16x32_bf16 v[124:127], v[24:27], v[218:221], v[124:127]
	v_mfma_f32_16x16x32_bf16 v[120:123], v[32:35], v[218:221], v[120:123]
	v_mfma_f32_16x16x32_bf16 v[108:111], v[24:27], v[226:229], v[108:111]
	v_mfma_f32_16x16x32_bf16 v[104:107], v[32:35], v[226:229], v[104:107]
	v_mfma_f32_16x16x32_bf16 v[92:95], v[24:27], v[234:237], v[92:95]
	v_mfma_f32_16x16x32_bf16 v[88:91], v[32:35], v[234:237], v[88:91]
	v_mfma_f32_16x16x32_bf16 v[140:143], v[28:31], v[214:217], v[140:143]
	v_mfma_f32_16x16x32_bf16 v[136:139], v[36:39], v[214:217], v[136:139]
	v_mfma_f32_16x16x32_bf16 v[124:127], v[28:31], v[222:225], v[124:127]
	v_mfma_f32_16x16x32_bf16 v[120:123], v[36:39], v[222:225], v[120:123]
	v_mfma_f32_16x16x32_bf16 v[108:111], v[28:31], v[230:233], v[108:111]
	v_mfma_f32_16x16x32_bf16 v[104:107], v[36:39], v[230:233], v[104:107]
	v_mfma_f32_16x16x32_bf16 v[92:95], v[28:31], v[238:241], v[92:95]
	v_mfma_f32_16x16x32_bf16 v[88:91], v[36:39], v[238:241], v[88:91]
	v_mfma_f32_16x16x32_bf16 v[132:135], v[160:163], v[210:213], v[132:135]
	v_mfma_f32_16x16x32_bf16 v[128:131], v[168:171], v[210:213], v[128:131]
	v_mfma_f32_16x16x32_bf16 v[116:119], v[160:163], v[218:221], v[116:119]
	v_mfma_f32_16x16x32_bf16 v[112:115], v[168:171], v[218:221], v[112:115]
	v_mfma_f32_16x16x32_bf16 v[100:103], v[160:163], v[226:229], v[100:103]
	v_mfma_f32_16x16x32_bf16 v[96:99], v[168:171], v[226:229], v[96:99]
	v_mfma_f32_16x16x32_bf16 v[84:87], v[160:163], v[234:237], v[84:87]
	v_mfma_f32_16x16x32_bf16 v[80:83], v[168:171], v[234:237], v[80:83]
	v_mfma_f32_16x16x32_bf16 v[132:135], v[164:167], v[214:217], v[132:135]
	v_mfma_f32_16x16x32_bf16 v[128:131], v[206:209], v[214:217], v[128:131]
	v_mfma_f32_16x16x32_bf16 v[116:119], v[164:167], v[222:225], v[116:119]
	v_mfma_f32_16x16x32_bf16 v[112:115], v[206:209], v[222:225], v[112:115]
	v_mfma_f32_16x16x32_bf16 v[100:103], v[164:167], v[230:233], v[100:103]
	v_mfma_f32_16x16x32_bf16 v[96:99], v[206:209], v[230:233], v[96:99]
	v_mfma_f32_16x16x32_bf16 v[84:87], v[164:167], v[238:241], v[84:87]
	v_mfma_f32_16x16x32_bf16 v[80:83], v[206:209], v[238:241], v[80:83]
	s_barrier
	s_add_i32 s75, s75, s44
	v_lshl_add_u64 v[172:173], s[76:77], 0, v[152:153]
	s_mov_b32 m0, s75
	ds_read_b128 v[210:213], v205 offset:16384
	ds_read_b128 v[214:217], v205 offset:17408
	ds_read_b128 v[218:221], v205 offset:18432
	ds_read_b128 v[222:225], v205 offset:19456
	ds_read_b128 v[226:229], v205 offset:20480
	ds_read_b128 v[230:233], v205 offset:21504
	ds_read_b128 v[234:237], v205 offset:22528
	ds_read_b128 v[238:241], v205 offset:23552
	global_load_lds_dwordx4 v[172:173], off
	s_add_i32 m0, s75, 0x2000
	v_lshl_add_u64 v[242:243], s[76:77], 0, v[148:149]
	s_add_u32 s76, s76, s0
	s_addc_u32 s77, s77, 0
	s_add_i32 s25, s25, s44
	global_load_lds_dwordx4 v[242:243], off
	v_lshl_add_u64 v[244:245], s[76:77], 0, v[152:153]
	s_mov_b32 m0, s25
	v_lshl_add_u64 v[246:247], s[76:77], 0, v[148:149]
	global_load_lds_dwordx4 v[244:245], off
	s_add_i32 m0, s25, 0x2000
	v_lshl_add_u64 v[248:249], s[22:23], 0, v[144:145]
	global_load_lds_dwordx4 v[246:247], off
	s_mov_b32 m0, s45
	v_lshl_add_u64 v[250:251], s[22:23], 0, v[146:147]
	global_load_lds_dwordx4 v[248:249], off
	s_mov_b32 m0, s48
	s_nop 0
	global_load_lds_dwordx4 v[250:251], off
	s_waitcnt vmcnt(8)
	s_waitcnt lgkmcnt(0)
	s_barrier
	s_waitcnt lgkmcnt(0)
	v_mfma_f32_16x16x32_bf16 v[76:79], v[24:27], v[210:213], v[76:79]
	v_mfma_f32_16x16x32_bf16 v[72:75], v[32:35], v[210:213], v[72:75]
	v_mfma_f32_16x16x32_bf16 v[60:63], v[24:27], v[218:221], v[60:63]
	v_mfma_f32_16x16x32_bf16 v[56:59], v[32:35], v[218:221], v[56:59]
	v_mfma_f32_16x16x32_bf16 v[44:47], v[24:27], v[226:229], v[44:47]
	v_mfma_f32_16x16x32_bf16 v[40:43], v[32:35], v[226:229], v[40:43]
	v_mfma_f32_16x16x32_bf16 v[12:15], v[24:27], v[234:237], v[12:15]
	v_mfma_f32_16x16x32_bf16 v[8:11], v[32:35], v[234:237], v[8:11]
	v_mfma_f32_16x16x32_bf16 v[76:79], v[28:31], v[214:217], v[76:79]
	v_mfma_f32_16x16x32_bf16 v[72:75], v[36:39], v[214:217], v[72:75]
	v_mfma_f32_16x16x32_bf16 v[60:63], v[28:31], v[222:225], v[60:63]
	v_mfma_f32_16x16x32_bf16 v[56:59], v[36:39], v[222:225], v[56:59]
	v_mfma_f32_16x16x32_bf16 v[44:47], v[28:31], v[230:233], v[44:47]
	v_mfma_f32_16x16x32_bf16 v[40:43], v[36:39], v[230:233], v[40:43]
	v_mfma_f32_16x16x32_bf16 v[12:15], v[28:31], v[238:241], v[12:15]
	v_mfma_f32_16x16x32_bf16 v[8:11], v[36:39], v[238:241], v[8:11]
	v_mfma_f32_16x16x32_bf16 v[20:23], v[160:163], v[226:229], v[20:23]
	v_mfma_f32_16x16x32_bf16 v[16:19], v[168:171], v[226:229], v[16:19]
	v_mfma_f32_16x16x32_bf16 v[4:7], v[160:163], v[234:237], v[4:7]
	v_mfma_f32_16x16x32_bf16 v[0:3], v[168:171], v[234:237], v[0:3]
	v_mfma_f32_16x16x32_bf16 v[24:27], v[160:163], v[210:213], v[68:71]
	v_mfma_f32_16x16x32_bf16 v[28:31], v[168:171], v[210:213], v[64:67]
	v_mfma_f32_16x16x32_bf16 v[32:35], v[160:163], v[218:221], v[52:55]
	v_mfma_f32_16x16x32_bf16 v[36:39], v[168:171], v[218:221], v[48:51]
	v_mfma_f32_16x16x32_bf16 v[20:23], v[164:167], v[230:233], v[20:23]
	v_mfma_f32_16x16x32_bf16 v[16:19], v[206:209], v[230:233], v[16:19]
	v_mfma_f32_16x16x32_bf16 v[4:7], v[164:167], v[238:241], v[4:7]
	v_mfma_f32_16x16x32_bf16 v[0:3], v[206:209], v[238:241], v[0:3]
	v_mfma_f32_16x16x32_bf16 v[24:27], v[164:167], v[214:217], v[24:27]
	v_mfma_f32_16x16x32_bf16 v[28:31], v[206:209], v[214:217], v[28:31]
	v_mfma_f32_16x16x32_bf16 v[32:35], v[164:167], v[222:225], v[32:35]
	v_mfma_f32_16x16x32_bf16 v[36:39], v[206:209], v[222:225], v[36:39]
	s_barrier
	s_add_i32 s25, 0, 0x18000
	s_add_i32 s75, 0, 0x1c000
	v_add_u32_e32 v68, s25, v203
	v_add_u32_e32 v184, s75, v203
	ds_read_b128 v[48:51], v68
	ds_read_b128 v[52:55], v68 offset:1024
	ds_read_b128 v[64:67], v68 offset:2048
	ds_read_b128 v[68:71], v68 offset:3072
	ds_read_b128 v[160:163], v184
	ds_read_b128 v[164:167], v184 offset:1024
	ds_read_b128 v[168:171], v184 offset:2048
	ds_read_b128 v[206:209], v184 offset:3072
	s_add_u32 s22, s22, s0
	s_addc_u32 s23, s23, 0
	s_mov_b32 m0, s49
	v_lshl_add_u64 v[184:185], s[22:23], 0, v[144:145]
	ds_read_b128 v[210:213], v205 offset:32768
	ds_read_b128 v[214:217], v205 offset:33792
	ds_read_b128 v[218:221], v205 offset:34816
	ds_read_b128 v[222:225], v205 offset:35840
	ds_read_b128 v[226:229], v205 offset:36864
	ds_read_b128 v[230:233], v205 offset:37888
	ds_read_b128 v[234:237], v205 offset:38912
	ds_read_b128 v[238:241], v205 offset:39936
	global_load_lds_dwordx4 v[184:185], off
	v_lshl_add_u64 v[184:185], s[22:23], 0, v[146:147]
	s_mov_b32 m0, s52
	s_nop 0
	global_load_lds_dwordx4 v[184:185], off
	s_waitcnt vmcnt(8)
	s_waitcnt lgkmcnt(0)
	s_barrier
	s_waitcnt lgkmcnt(0)
	v_mfma_f32_16x16x32_bf16 v[140:143], v[48:51], v[210:213], v[140:143]
	v_mfma_f32_16x16x32_bf16 v[136:139], v[64:67], v[210:213], v[136:139]
	v_mfma_f32_16x16x32_bf16 v[124:127], v[48:51], v[218:221], v[124:127]
	v_mfma_f32_16x16x32_bf16 v[120:123], v[64:67], v[218:221], v[120:123]
	v_mfma_f32_16x16x32_bf16 v[108:111], v[48:51], v[226:229], v[108:111]
	v_mfma_f32_16x16x32_bf16 v[104:107], v[64:67], v[226:229], v[104:107]
	v_mfma_f32_16x16x32_bf16 v[92:95], v[48:51], v[234:237], v[92:95]
	v_mfma_f32_16x16x32_bf16 v[88:91], v[64:67], v[234:237], v[88:91]
	v_mfma_f32_16x16x32_bf16 v[140:143], v[52:55], v[214:217], v[140:143]
	v_mfma_f32_16x16x32_bf16 v[136:139], v[68:71], v[214:217], v[136:139]
	v_mfma_f32_16x16x32_bf16 v[124:127], v[52:55], v[222:225], v[124:127]
	v_mfma_f32_16x16x32_bf16 v[120:123], v[68:71], v[222:225], v[120:123]
	v_mfma_f32_16x16x32_bf16 v[108:111], v[52:55], v[230:233], v[108:111]
	v_mfma_f32_16x16x32_bf16 v[104:107], v[68:71], v[230:233], v[104:107]
	v_mfma_f32_16x16x32_bf16 v[92:95], v[52:55], v[238:241], v[92:95]
	v_mfma_f32_16x16x32_bf16 v[88:91], v[68:71], v[238:241], v[88:91]
	v_mfma_f32_16x16x32_bf16 v[132:135], v[160:163], v[210:213], v[132:135]
	v_mfma_f32_16x16x32_bf16 v[128:131], v[168:171], v[210:213], v[128:131]
	v_mfma_f32_16x16x32_bf16 v[116:119], v[160:163], v[218:221], v[116:119]
	v_mfma_f32_16x16x32_bf16 v[112:115], v[168:171], v[218:221], v[112:115]
	v_mfma_f32_16x16x32_bf16 v[100:103], v[160:163], v[226:229], v[100:103]
	v_mfma_f32_16x16x32_bf16 v[96:99], v[168:171], v[226:229], v[96:99]
	v_mfma_f32_16x16x32_bf16 v[84:87], v[160:163], v[234:237], v[84:87]
	v_mfma_f32_16x16x32_bf16 v[80:83], v[168:171], v[234:237], v[80:83]
	v_mfma_f32_16x16x32_bf16 v[132:135], v[164:167], v[214:217], v[132:135]
	v_mfma_f32_16x16x32_bf16 v[128:131], v[206:209], v[214:217], v[128:131]
	v_mfma_f32_16x16x32_bf16 v[116:119], v[164:167], v[222:225], v[116:119]
	v_mfma_f32_16x16x32_bf16 v[112:115], v[206:209], v[222:225], v[112:115]
	v_mfma_f32_16x16x32_bf16 v[100:103], v[164:167], v[230:233], v[100:103]
	v_mfma_f32_16x16x32_bf16 v[96:99], v[206:209], v[230:233], v[96:99]
	v_mfma_f32_16x16x32_bf16 v[84:87], v[164:167], v[238:241], v[84:87]
	v_mfma_f32_16x16x32_bf16 v[80:83], v[206:209], v[238:241], v[80:83]
	s_barrier
	s_add_i32 s22, s25, s44
	v_lshl_add_u64 v[172:173], v[172:173], 0, s[26:27]
	s_mov_b32 m0, s22
	ds_read_b128 v[210:213], v205 offset:49152
	ds_read_b128 v[214:217], v205 offset:50176
	ds_read_b128 v[218:221], v205 offset:51200
	ds_read_b128 v[222:225], v205 offset:52224
	ds_read_b128 v[226:229], v205 offset:53248
	ds_read_b128 v[230:233], v205 offset:54272
	ds_read_b128 v[234:237], v205 offset:55296
	ds_read_b128 v[238:241], v205 offset:56320
	global_load_lds_dwordx4 v[172:173], off
	v_lshl_add_u64 v[172:173], v[242:243], 0, s[26:27]
	s_add_i32 m0, s22, 0x2000
	s_add_i32 s22, s75, s44
	global_load_lds_dwordx4 v[172:173], off
	v_lshl_add_u64 v[172:173], v[244:245], 0, s[26:27]
	s_mov_b32 m0, s22
	s_nop 0
	global_load_lds_dwordx4 v[172:173], off
	v_lshl_add_u64 v[172:173], v[246:247], 0, s[26:27]
	s_add_i32 m0, s22, 0x2000
	s_nop 0
	global_load_lds_dwordx4 v[172:173], off
	v_lshl_add_u64 v[172:173], v[248:249], 0, s[26:27]
	s_mov_b32 m0, s53
	s_nop 0
	global_load_lds_dwordx4 v[172:173], off
	v_lshl_add_u64 v[172:173], v[250:251], 0, s[26:27]
	s_mov_b32 m0, s54
	s_nop 0
	global_load_lds_dwordx4 v[172:173], off
	s_waitcnt vmcnt(8)
	s_waitcnt lgkmcnt(0)
	s_barrier
	s_waitcnt lgkmcnt(0)
	v_mfma_f32_16x16x32_bf16 v[76:79], v[48:51], v[210:213], v[76:79]
	v_mfma_f32_16x16x32_bf16 v[72:75], v[64:67], v[210:213], v[72:75]
	v_mfma_f32_16x16x32_bf16 v[60:63], v[48:51], v[218:221], v[60:63]
	v_mfma_f32_16x16x32_bf16 v[56:59], v[64:67], v[218:221], v[56:59]
	v_mfma_f32_16x16x32_bf16 v[44:47], v[48:51], v[226:229], v[44:47]
	v_mfma_f32_16x16x32_bf16 v[40:43], v[64:67], v[226:229], v[40:43]
	v_mfma_f32_16x16x32_bf16 v[12:15], v[48:51], v[234:237], v[12:15]
	v_mfma_f32_16x16x32_bf16 v[8:11], v[64:67], v[234:237], v[8:11]
	v_mfma_f32_16x16x32_bf16 v[76:79], v[52:55], v[214:217], v[76:79]
	v_mfma_f32_16x16x32_bf16 v[72:75], v[68:71], v[214:217], v[72:75]
	v_mfma_f32_16x16x32_bf16 v[60:63], v[52:55], v[222:225], v[60:63]
	v_mfma_f32_16x16x32_bf16 v[56:59], v[68:71], v[222:225], v[56:59]
	v_mfma_f32_16x16x32_bf16 v[44:47], v[52:55], v[230:233], v[44:47]
	v_mfma_f32_16x16x32_bf16 v[40:43], v[68:71], v[230:233], v[40:43]
	v_mfma_f32_16x16x32_bf16 v[12:15], v[52:55], v[238:241], v[12:15]
	v_mfma_f32_16x16x32_bf16 v[8:11], v[68:71], v[238:241], v[8:11]
	v_mfma_f32_16x16x32_bf16 v[24:27], v[160:163], v[210:213], v[24:27]
	v_mfma_f32_16x16x32_bf16 v[68:71], v[164:167], v[214:217], v[24:27]
	v_mfma_f32_16x16x32_bf16 v[24:27], v[168:171], v[210:213], v[28:31]
	v_mfma_f32_16x16x32_bf16 v[64:67], v[206:209], v[214:217], v[24:27]
	v_mfma_f32_16x16x32_bf16 v[24:27], v[160:163], v[218:221], v[32:35]
	v_mfma_f32_16x16x32_bf16 v[52:55], v[164:167], v[222:225], v[24:27]
	v_mfma_f32_16x16x32_bf16 v[24:27], v[168:171], v[218:221], v[36:39]
	v_mfma_f32_16x16x32_bf16 v[20:23], v[160:163], v[226:229], v[20:23]
	v_mfma_f32_16x16x32_bf16 v[16:19], v[168:171], v[226:229], v[16:19]
	v_mfma_f32_16x16x32_bf16 v[4:7], v[160:163], v[234:237], v[4:7]
	v_mfma_f32_16x16x32_bf16 v[0:3], v[168:171], v[234:237], v[0:3]
	v_mfma_f32_16x16x32_bf16 v[48:51], v[206:209], v[222:225], v[24:27]
	v_mfma_f32_16x16x32_bf16 v[20:23], v[164:167], v[230:233], v[20:23]
	v_mfma_f32_16x16x32_bf16 v[16:19], v[206:209], v[230:233], v[16:19]
	v_mfma_f32_16x16x32_bf16 v[4:7], v[164:167], v[238:241], v[4:7]
	v_mfma_f32_16x16x32_bf16 v[0:3], v[206:209], v[238:241], v[0:3]
	s_barrier
	s_add_u32 s73, s73, 0x100
	s_addc_u32 s74, s74, 0
	s_add_u32 s4, s4, 0x100
	s_addc_u32 s5, s5, 0
	s_cmp_ge_u32 s24, s55
	s_mov_b32 s22, s24
	s_cbranch_scc0 .LBB0_589
	s_and_b64 vcc, exec, s[14:15]
	s_cbranch_vccz .LBB0_592
	s_barrier

.LBB0_736:
	s_add_u32 s28, s24, 0xfffc0080
	s_addc_u32 s29, s25, -1
	s_add_i32 s67, 0, 0x10000
	s_cmp_eq_u32 s66, 12
	s_cselect_b32 s31, s17, s29
	s_cselect_b32 s30, s62, s28
	v_add_u32_e32 v150, s67, v139
	s_cselect_b32 s29, s15, s65
	s_cselect_b32 s28, s63, s64
	s_add_i32 s70, 0, 0x14000
	ds_read_b128 v[142:145], v150
	ds_read_b128 v[146:149], v150 offset:1024
	ds_read_b128 v[158:161], v150 offset:2048
	ds_read_b128 v[162:165], v150 offset:3072
	v_add_u32_e32 v150, s70, v139
	ds_read_b128 v[166:169], v150
	ds_read_b128 v[170:173], v150 offset:1024
	ds_read_b128 v[178:181], v150 offset:2048
	ds_read_b128 v[192:195], v150 offset:3072
	v_lshl_add_u64 v[150:151], s[24:25], 0, v[136:137]
	s_add_i32 m0, s19, 0xc000
	ds_read_b128 v[196:199], v141
	ds_read_b128 v[200:203], v141 offset:1024
	ds_read_b128 v[204:207], v141 offset:2048
	ds_read_b128 v[208:211], v141 offset:3072
	ds_read_b128 v[212:215], v141 offset:4096
	ds_read_b128 v[216:219], v141 offset:5120
	ds_read_b128 v[220:223], v141 offset:6144
	ds_read_b128 v[224:227], v141 offset:7168
	global_load_lds_dwordx4 v[150:151], off
	v_lshl_add_u64 v[150:151], s[24:25], 0, v[132:133]
	s_add_i32 m0, s19, 0xe000
	s_nop 0
	global_load_lds_dwordx4 v[150:151], off
	s_waitcnt vmcnt(8)
	s_waitcnt lgkmcnt(0)
	s_barrier
	s_waitcnt lgkmcnt(0)
	v_mfma_f32_16x16x32_bf16 v[124:127], v[142:145], v[196:199], v[124:127]
	v_mfma_f32_16x16x32_bf16 v[120:123], v[158:161], v[196:199], v[120:123]
	v_mfma_f32_16x16x32_bf16 v[116:119], v[142:145], v[204:207], v[116:119]
	v_mfma_f32_16x16x32_bf16 v[112:115], v[158:161], v[204:207], v[112:115]
	v_mfma_f32_16x16x32_bf16 v[100:103], v[142:145], v[212:215], v[100:103]
	v_mfma_f32_16x16x32_bf16 v[96:99], v[158:161], v[212:215], v[96:99]
	v_mfma_f32_16x16x32_bf16 v[84:87], v[142:145], v[220:223], v[84:87]
	v_mfma_f32_16x16x32_bf16 v[80:83], v[158:161], v[220:223], v[80:83]
	v_mfma_f32_16x16x32_bf16 v[124:127], v[146:149], v[200:203], v[124:127]
	v_mfma_f32_16x16x32_bf16 v[120:123], v[162:165], v[200:203], v[120:123]
	v_mfma_f32_16x16x32_bf16 v[116:119], v[146:149], v[208:211], v[116:119]
	v_mfma_f32_16x16x32_bf16 v[112:115], v[162:165], v[208:211], v[112:115]
	v_mfma_f32_16x16x32_bf16 v[100:103], v[146:149], v[216:219], v[100:103]
	v_mfma_f32_16x16x32_bf16 v[96:99], v[162:165], v[216:219], v[96:99]
	v_mfma_f32_16x16x32_bf16 v[84:87], v[146:149], v[224:227], v[84:87]
	v_mfma_f32_16x16x32_bf16 v[80:83], v[162:165], v[224:227], v[80:83]
	v_mfma_f32_16x16x32_bf16 v[108:111], v[166:169], v[196:199], v[108:111]
	v_mfma_f32_16x16x32_bf16 v[104:107], v[178:181], v[196:199], v[104:107]
	v_mfma_f32_16x16x32_bf16 v[92:95], v[166:169], v[204:207], v[92:95]
	v_mfma_f32_16x16x32_bf16 v[88:91], v[178:181], v[204:207], v[88:91]
	v_mfma_f32_16x16x32_bf16 v[76:79], v[166:169], v[212:215], v[76:79]
	v_mfma_f32_16x16x32_bf16 v[72:75], v[178:181], v[212:215], v[72:75]
	v_mfma_f32_16x16x32_bf16 v[68:71], v[166:169], v[220:223], v[68:71]
	v_mfma_f32_16x16x32_bf16 v[64:67], v[178:181], v[220:223], v[64:67]
	v_mfma_f32_16x16x32_bf16 v[108:111], v[170:173], v[200:203], v[108:111]
	v_mfma_f32_16x16x32_bf16 v[104:107], v[192:195], v[200:203], v[104:107]
	v_mfma_f32_16x16x32_bf16 v[92:95], v[170:173], v[208:211], v[92:95]
	v_mfma_f32_16x16x32_bf16 v[88:91], v[192:195], v[208:211], v[88:91]
	v_mfma_f32_16x16x32_bf16 v[76:79], v[170:173], v[216:219], v[76:79]
	v_mfma_f32_16x16x32_bf16 v[72:75], v[192:195], v[216:219], v[72:75]
	v_mfma_f32_16x16x32_bf16 v[68:71], v[170:173], v[224:227], v[68:71]
	v_mfma_f32_16x16x32_bf16 v[64:67], v[192:195], v[224:227], v[64:67]
	s_barrier
	s_add_i32 s67, s67, s46
	v_lshl_add_u64 v[150:151], s[28:29], 0, v[130:131]
	s_mov_b32 m0, s67
	ds_read_b128 v[196:199], v141 offset:16384
	ds_read_b128 v[200:203], v141 offset:17408
	ds_read_b128 v[204:207], v141 offset:18432
	ds_read_b128 v[208:211], v141 offset:19456
	ds_read_b128 v[212:215], v141 offset:20480
	ds_read_b128 v[216:219], v141 offset:21504
	ds_read_b128 v[220:223], v141 offset:22528
	ds_read_b128 v[224:227], v141 offset:23552
	global_load_lds_dwordx4 v[150:151], off
	s_add_i32 m0, s67, 0x2000
	s_add_u32 s68, s28, 0x40000
	v_lshl_add_u64 v[184:185], s[28:29], 0, v[134:135]
	s_addc_u32 s69, s29, 0
	s_add_i32 s67, s70, s46
	global_load_lds_dwordx4 v[184:185], off
	v_lshl_add_u64 v[228:229], s[68:69], 0, v[130:131]
	s_mov_b32 m0, s67
	v_lshl_add_u64 v[230:231], s[30:31], 0, v[132:133]
	global_load_lds_dwordx4 v[228:229], off
	v_lshl_add_u64 v[228:229], s[68:69], 0, v[134:135]
	s_add_i32 m0, s67, 0x2000
	s_nop 0
	global_load_lds_dwordx4 v[228:229], off
	v_lshl_add_u64 v[228:229], s[30:31], 0, v[128:129]
	s_mov_b32 m0, s19
	s_nop 0
	global_load_lds_dwordx4 v[228:229], off
	s_mov_b32 m0, s47
	s_nop 0
	global_load_lds_dwordx4 v[230:231], off
	s_waitcnt vmcnt(8)
	s_waitcnt lgkmcnt(0)
	s_barrier
	s_waitcnt lgkmcnt(0)
	v_mfma_f32_16x16x32_bf16 v[60:63], v[142:145], v[196:199], v[60:63]
	v_mfma_f32_16x16x32_bf16 v[56:59], v[158:161], v[196:199], v[56:59]
	v_mfma_f32_16x16x32_bf16 v[52:55], v[142:145], v[204:207], v[52:55]
	v_mfma_f32_16x16x32_bf16 v[48:51], v[158:161], v[204:207], v[48:51]
	v_mfma_f32_16x16x32_bf16 v[36:39], v[142:145], v[212:215], v[36:39]
	v_mfma_f32_16x16x32_bf16 v[32:35], v[158:161], v[212:215], v[32:35]
	v_mfma_f32_16x16x32_bf16 v[20:23], v[142:145], v[220:223], v[20:23]
	v_mfma_f32_16x16x32_bf16 v[16:19], v[158:161], v[220:223], v[16:19]
	v_mfma_f32_16x16x32_bf16 v[60:63], v[146:149], v[200:203], v[60:63]
	v_mfma_f32_16x16x32_bf16 v[56:59], v[162:165], v[200:203], v[56:59]
	v_mfma_f32_16x16x32_bf16 v[52:55], v[146:149], v[208:211], v[52:55]
	v_mfma_f32_16x16x32_bf16 v[48:51], v[162:165], v[208:211], v[48:51]
	v_mfma_f32_16x16x32_bf16 v[36:39], v[146:149], v[216:219], v[36:39]
	v_mfma_f32_16x16x32_bf16 v[32:35], v[162:165], v[216:219], v[32:35]
	v_mfma_f32_16x16x32_bf16 v[20:23], v[146:149], v[224:227], v[20:23]
	v_mfma_f32_16x16x32_bf16 v[16:19], v[162:165], v[224:227], v[16:19]
	v_mfma_f32_16x16x32_bf16 v[44:47], v[166:169], v[196:199], v[44:47]
	v_mfma_f32_16x16x32_bf16 v[40:43], v[178:181], v[196:199], v[40:43]
	v_mfma_f32_16x16x32_bf16 v[28:31], v[166:169], v[204:207], v[28:31]
	v_mfma_f32_16x16x32_bf16 v[24:27], v[178:181], v[204:207], v[24:27]
	v_mfma_f32_16x16x32_bf16 v[12:15], v[166:169], v[212:215], v[12:15]
	v_mfma_f32_16x16x32_bf16 v[8:11], v[178:181], v[212:215], v[8:11]
	v_mfma_f32_16x16x32_bf16 v[4:7], v[166:169], v[220:223], v[4:7]
	v_mfma_f32_16x16x32_bf16 v[0:3], v[178:181], v[220:223], v[0:3]
	v_mfma_f32_16x16x32_bf16 v[44:47], v[170:173], v[200:203], v[44:47]
	v_mfma_f32_16x16x32_bf16 v[40:43], v[192:195], v[200:203], v[40:43]
	v_mfma_f32_16x16x32_bf16 v[28:31], v[170:173], v[208:211], v[28:31]
	v_mfma_f32_16x16x32_bf16 v[24:27], v[192:195], v[208:211], v[24:27]
	v_mfma_f32_16x16x32_bf16 v[12:15], v[170:173], v[216:219], v[12:15]
	v_mfma_f32_16x16x32_bf16 v[8:11], v[192:195], v[216:219], v[8:11]
	v_mfma_f32_16x16x32_bf16 v[4:7], v[170:173], v[224:227], v[4:7]
	v_mfma_f32_16x16x32_bf16 v[0:3], v[192:195], v[224:227], v[0:3]
	s_barrier
	s_add_i32 s67, 0, 0x18000
	v_add_u32_e32 v152, s67, v139
	s_add_i32 s68, 0, 0x1c000
	ds_read_b128 v[142:145], v152
	ds_read_b128 v[146:149], v152 offset:1024
	ds_read_b128 v[158:161], v152 offset:2048
	ds_read_b128 v[162:165], v152 offset:3072
	v_add_u32_e32 v152, s68, v139
	ds_read_b128 v[166:169], v152
	ds_read_b128 v[170:173], v152 offset:1024
	ds_read_b128 v[178:181], v152 offset:2048
	ds_read_b128 v[192:195], v152 offset:3072
	s_add_u32 s30, s30, 0x40000
	s_addc_u32 s31, s31, 0
	s_mov_b32 m0, s48
	v_lshl_add_u64 v[232:233], s[30:31], 0, v[128:129]
	ds_read_b128 v[196:199], v141 offset:32768
	ds_read_b128 v[200:203], v141 offset:33792
	ds_read_b128 v[204:207], v141 offset:34816
	ds_read_b128 v[208:211], v141 offset:35840
	ds_read_b128 v[212:215], v141 offset:36864
	ds_read_b128 v[216:219], v141 offset:37888
	ds_read_b128 v[220:223], v141 offset:38912
	ds_read_b128 v[224:227], v141 offset:39936
	global_load_lds_dwordx4 v[232:233], off
	v_lshl_add_u64 v[232:233], s[30:31], 0, v[132:133]
	s_mov_b32 m0, s49
	s_nop 0
	global_load_lds_dwordx4 v[232:233], off
	s_waitcnt vmcnt(8)
	s_waitcnt lgkmcnt(0)
	s_barrier
	s_waitcnt lgkmcnt(0)
	v_mfma_f32_16x16x32_bf16 v[124:127], v[142:145], v[196:199], v[124:127]
	v_mfma_f32_16x16x32_bf16 v[120:123], v[158:161], v[196:199], v[120:123]
	v_mfma_f32_16x16x32_bf16 v[116:119], v[142:145], v[204:207], v[116:119]
	v_mfma_f32_16x16x32_bf16 v[112:115], v[158:161], v[204:207], v[112:115]
	v_mfma_f32_16x16x32_bf16 v[100:103], v[142:145], v[212:215], v[100:103]
	v_mfma_f32_16x16x32_bf16 v[96:99], v[158:161], v[212:215], v[96:99]
	v_mfma_f32_16x16x32_bf16 v[84:87], v[142:145], v[220:223], v[84:87]
	v_mfma_f32_16x16x32_bf16 v[80:83], v[158:161], v[220:223], v[80:83]
	v_mfma_f32_16x16x32_bf16 v[124:127], v[146:149], v[200:203], v[124:127]
	v_mfma_f32_16x16x32_bf16 v[120:123], v[162:165], v[200:203], v[120:123]
	v_mfma_f32_16x16x32_bf16 v[116:119], v[146:149], v[208:211], v[116:119]
	v_mfma_f32_16x16x32_bf16 v[112:115], v[162:165], v[208:211], v[112:115]
	v_mfma_f32_16x16x32_bf16 v[100:103], v[146:149], v[216:219], v[100:103]
	v_mfma_f32_16x16x32_bf16 v[96:99], v[162:165], v[216:219], v[96:99]
	v_mfma_f32_16x16x32_bf16 v[84:87], v[146:149], v[224:227], v[84:87]
	v_mfma_f32_16x16x32_bf16 v[80:83], v[162:165], v[224:227], v[80:83]
	v_mfma_f32_16x16x32_bf16 v[108:111], v[166:169], v[196:199], v[108:111]
	v_mfma_f32_16x16x32_bf16 v[104:107], v[178:181], v[196:199], v[104:107]
	v_mfma_f32_16x16x32_bf16 v[92:95], v[166:169], v[204:207], v[92:95]
	v_mfma_f32_16x16x32_bf16 v[88:91], v[178:181], v[204:207], v[88:91]
	v_mfma_f32_16x16x32_bf16 v[76:79], v[166:169], v[212:215], v[76:79]
	v_mfma_f32_16x16x32_bf16 v[72:75], v[178:181], v[212:215], v[72:75]
	v_mfma_f32_16x16x32_bf16 v[68:71], v[166:169], v[220:223], v[68:71]
	v_mfma_f32_16x16x32_bf16 v[64:67], v[178:181], v[220:223], v[64:67]
	v_mfma_f32_16x16x32_bf16 v[108:111], v[170:173], v[200:203], v[108:111]
	v_mfma_f32_16x16x32_bf16 v[104:107], v[192:195], v[200:203], v[104:107]
	v_mfma_f32_16x16x32_bf16 v[92:95], v[170:173], v[208:211], v[92:95]
	v_mfma_f32_16x16x32_bf16 v[88:91], v[192:195], v[208:211], v[88:91]
	v_mfma_f32_16x16x32_bf16 v[76:79], v[170:173], v[216:219], v[76:79]
	v_mfma_f32_16x16x32_bf16 v[72:75], v[192:195], v[216:219], v[72:75]
	v_mfma_f32_16x16x32_bf16 v[68:71], v[170:173], v[224:227], v[68:71]
	v_mfma_f32_16x16x32_bf16 v[64:67], v[192:195], v[224:227], v[64:67]
	s_barrier
	s_add_i32 s30, s67, s46
	v_lshl_add_u64 v[150:151], v[150:151], 0, s[26:27]
	s_mov_b32 m0, s30
	ds_read_b128 v[196:199], v141 offset:49152
	ds_read_b128 v[200:203], v141 offset:50176
	ds_read_b128 v[204:207], v141 offset:51200
	ds_read_b128 v[208:211], v141 offset:52224
	ds_read_b128 v[212:215], v141 offset:53248
	ds_read_b128 v[216:219], v141 offset:54272
	ds_read_b128 v[220:223], v141 offset:55296
	ds_read_b128 v[224:227], v141 offset:56320
	global_load_lds_dwordx4 v[150:151], off
	s_add_i32 m0, s30, 0x2000
	s_add_u32 s28, s28, 0x40080
	v_lshl_add_u64 v[150:151], v[184:185], 0, s[26:27]
	s_addc_u32 s29, s29, 0
	s_add_i32 s30, s68, s46
	global_load_lds_dwordx4 v[150:151], off
	v_lshl_add_u64 v[150:151], s[28:29], 0, v[130:131]
	s_mov_b32 m0, s30
	s_nop 0
	global_load_lds_dwordx4 v[150:151], off
	v_lshl_add_u64 v[150:151], s[28:29], 0, v[134:135]
	s_add_i32 m0, s30, 0x2000
	s_nop 0
	global_load_lds_dwordx4 v[150:151], off
	v_lshl_add_u64 v[150:151], v[228:229], 0, s[26:27]
	s_mov_b32 m0, s54
	s_nop 0
	global_load_lds_dwordx4 v[150:151], off
	v_lshl_add_u64 v[150:151], v[230:231], 0, s[26:27]
	s_mov_b32 m0, s55
	s_nop 0
	global_load_lds_dwordx4 v[150:151], off
	s_waitcnt vmcnt(8)
	s_waitcnt lgkmcnt(0)
	s_barrier
	s_waitcnt lgkmcnt(0)
	v_mfma_f32_16x16x32_bf16 v[60:63], v[142:145], v[196:199], v[60:63]
	v_mfma_f32_16x16x32_bf16 v[56:59], v[158:161], v[196:199], v[56:59]
	v_mfma_f32_16x16x32_bf16 v[52:55], v[142:145], v[204:207], v[52:55]
	v_mfma_f32_16x16x32_bf16 v[48:51], v[158:161], v[204:207], v[48:51]
	v_mfma_f32_16x16x32_bf16 v[36:39], v[142:145], v[212:215], v[36:39]
	v_mfma_f32_16x16x32_bf16 v[32:35], v[158:161], v[212:215], v[32:35]
	v_mfma_f32_16x16x32_bf16 v[20:23], v[142:145], v[220:223], v[20:23]
	v_mfma_f32_16x16x32_bf16 v[16:19], v[158:161], v[220:223], v[16:19]
	v_mfma_f32_16x16x32_bf16 v[60:63], v[146:149], v[200:203], v[60:63]
	v_mfma_f32_16x16x32_bf16 v[56:59], v[162:165], v[200:203], v[56:59]
	v_mfma_f32_16x16x32_bf16 v[52:55], v[146:149], v[208:211], v[52:55]
	v_mfma_f32_16x16x32_bf16 v[48:51], v[162:165], v[208:211], v[48:51]
	v_mfma_f32_16x16x32_bf16 v[36:39], v[146:149], v[216:219], v[36:39]
	v_mfma_f32_16x16x32_bf16 v[32:35], v[162:165], v[216:219], v[32:35]
	v_mfma_f32_16x16x32_bf16 v[20:23], v[146:149], v[224:227], v[20:23]
	v_mfma_f32_16x16x32_bf16 v[16:19], v[162:165], v[224:227], v[16:19]
	v_mfma_f32_16x16x32_bf16 v[44:47], v[166:169], v[196:199], v[44:47]
	v_mfma_f32_16x16x32_bf16 v[40:43], v[178:181], v[196:199], v[40:43]
	v_mfma_f32_16x16x32_bf16 v[28:31], v[166:169], v[204:207], v[28:31]
	v_mfma_f32_16x16x32_bf16 v[24:27], v[178:181], v[204:207], v[24:27]
	v_mfma_f32_16x16x32_bf16 v[12:15], v[166:169], v[212:215], v[12:15]
	v_mfma_f32_16x16x32_bf16 v[8:11], v[178:181], v[212:215], v[8:11]
	v_mfma_f32_16x16x32_bf16 v[4:7], v[166:169], v[220:223], v[4:7]
	v_mfma_f32_16x16x32_bf16 v[0:3], v[178:181], v[220:223], v[0:3]
	v_mfma_f32_16x16x32_bf16 v[44:47], v[170:173], v[200:203], v[44:47]
	v_mfma_f32_16x16x32_bf16 v[40:43], v[192:195], v[200:203], v[40:43]
	v_mfma_f32_16x16x32_bf16 v[28:31], v[170:173], v[208:211], v[28:31]
	v_mfma_f32_16x16x32_bf16 v[24:27], v[192:195], v[208:211], v[24:27]
	v_mfma_f32_16x16x32_bf16 v[12:15], v[170:173], v[216:219], v[12:15]
	v_mfma_f32_16x16x32_bf16 v[8:11], v[192:195], v[216:219], v[8:11]
	v_mfma_f32_16x16x32_bf16 v[4:7], v[170:173], v[224:227], v[4:7]
	v_mfma_f32_16x16x32_bf16 v[0:3], v[192:195], v[224:227], v[0:3]
	s_barrier
	s_add_i32 s66, s66, 2
	s_add_u32 s64, s64, 0x100
	s_addc_u32 s65, s65, 0
	s_add_u32 s24, s24, 0x100
	s_addc_u32 s25, s25, 0
	s_cmp_gt_u32 s66, 13
	s_cbranch_scc0 .LBB0_736
	s_and_b64 vcc, exec, s[10:11]
	s_cbranch_vccz .LBB0_739
	s_barrier
